# v5 + hand-written rope epilogue (modes 2/3): rope values loaded once per tile, permlane16_swap lane exchange, no per-block drains
# speedup vs baseline: 1.0206x; 1.0117x over previous
; __device__ __forceinline__ void epi_store(const f32x4 (&acc)[2][2][4][2], const Unit& u, int wr, int wc, int fr, int fq, const EpiP& e) {
;     ...
;     const int col0 = u.pn * BM + wc * 32 + 4 * fq;
; #pragma unroll
;     for (int bj = 0; bj < 2; ++bj) {
;         const int c = col0 + bj * HALF;
;         int kind = 0;
;         if (e.mode == 2) { if (c < 2048) kind = ((c >> 5) & 1) ? 2 : 1; }
;         else { const int d = c % 192; if (d >= 128) kind = (d >= 160) ? 2 : 1; }
; #pragma unroll
;         for (int ai = 0; ai < 2; ++ai)
; #pragma unroll
;             for (int m = 0; m < 4; ++m) {
;                 const int row = row0 + ai * HALF + m * 16;
;                 f32x4 v0 = acc[ai][bj][m][0], v1 = acc[ai][bj][m][1];
;                 if (kind != 0 && row < MLAT) {
;                     const int t = row & (SEQ - 1); const int pos = (kind == 1) ? (t >> 6) : (t & 63);
;                     const f32x4 t0 = *(const f32x4*)(e.rope + (pos * 16 + 4 * fq) * 2), t1 = *(const f32x4*)(e.rope + (pos * 16 + 4 * fq) * 2 + 4);
.LBB0_397:
	s_lshl_b32 s18, s87, 8
	v_readlane_b32 s3, v254, 56
	v_readlane_b32 s20, v255, 11
	s_add_i32 s18, s18, s3
	v_readlane_b32 s21, v255, 12
	v_or_b32_e32 v98, s18, v151
	s_lshl_b32 s43, s85, 8
	s_mov_b64 s[16:17], -1
	s_and_b64 vcc, exec, s[20:21]
	s_cbranch_vccz .LBB0_440
	v_readfirstlane_b32 s16, v159
	v_and_b32_e32 v217, 15, v159
	v_bfe_u32 v219, v159, 4, 2
	s_lshr_b32 s16, s16, 6
	s_and_b32 s17, s16, 3
	s_lshr_b32 s16, s16, 2
	s_mul_i32 s18, s87, s70
	s_lshl_b32 s18, s18, 9
	s_lshl_b32 s19, s85, 9
	s_add_u32 s18, s18, s19
	s_add_u32 s100, s74, s18
	s_addc_u32 s101, s75, 0
	s_lshl_b32 s18, s16, 6
	v_or_b32_e32 v218, s18, v217
	v_mul_lo_u32 v218, v218, s70
	v_and_b32_e32 v220, 1, v219
	v_mul_u32_u24_e32 v220, 12, v220
	v_lshl_add_u32 v220, v219, 2, v220
	s_lshl_b32 s18, s17, 5
	v_add_u32_e32 v220, s18, v220
	v_add_lshl_u32 v216, v218, v220, 1
	s_lshl_b32 s19, s70, 5
	v_lshlrev_b32_e32 v221, 5, v219
	v_lshl_or_b32 v222, v217, 7, v221
	v_readlane_b32 s22, v255, 15
	v_readlane_b32 s23, v255, 16
	s_and_b64 vcc, exec, s[22:23]
	s_cbranch_vccnz .Lrp_m3
	s_and_b32 s20, s17, 1
	s_add_i32 s20, s20, 1
	s_cmp_lt_u32 s85, 8
	s_cselect_b32 s20, s20, 0
	s_mov_b32 s21, s20
	s_branch .Lrp_kdone
.Lrp_m3:
	s_lshl_b32 s18, s85, 3
	s_add_i32 s18, s18, s17
	s_mul_i32 s26, s18, 43
	s_lshr_b32 s26, s26, 8
	s_mul_i32 s26, s26, 6
	s_sub_i32 s18, s18, s26
	s_sub_i32 s18, s18, 3
	s_max_i32 s20, s18, 0
	s_lshl_b32 s18, s85, 3
	s_add_i32 s18, s18, s17
	s_add_i32 s18, s18, 4
	s_mul_i32 s26, s18, 43
	s_lshr_b32 s26, s26, 8
	s_mul_i32 s26, s26, 6
	s_sub_i32 s18, s18, s26
	s_sub_i32 s18, s18, 3
	s_max_i32 s21, s18, 0
.Lrp_kdone:
	s_cmp_lt_u32 s87, 0x80
	s_cselect_b32 s20, s20, 0
	s_cselect_b32 s21, s21, 0
	s_or_b32 s27, s20, s21
	s_cmp_eq_u32 s27, 0
	s_cbranch_scc1 .Lrp_loaded
	v_readlane_b32 s22, v253, 6
	v_readlane_b32 s23, v253, 7
	s_cmp_eq_u32 s27, 1
	s_cbranch_scc0 .Lrp_ld2
	s_lshl_b32 s18, s87, 2
	s_add_i32 s18, s18, s16
	s_and_b32 s26, s18, 31
	s_lshl_b32 s26, s26, 7
	s_add_u32 s24, s22, s26
	s_addc_u32 s25, s23, 0
	s_add_i32 s18, s18, 2
	s_and_b32 s26, s18, 31
	s_lshl_b32 s26, s26, 7
	s_add_u32 s22, s22, s26
	s_addc_u32 s23, s23, 0
	global_load_dwordx4 v[160:163], v221, s[24:25]
	global_load_dwordx4 v[164:167], v221, s[24:25] offset:16
	global_load_dwordx4 v[168:171], v221, s[22:23]
	global_load_dwordx4 v[172:175], v221, s[22:23] offset:16
	s_branch .Lrp_ldw
.Lrp_ld2:
	s_add_u32 s24, s22, 0x1000
	s_addc_u32 s25, s23, 0
	global_load_dwordx4 v[160:163], v222, s[22:23]
	global_load_dwordx4 v[164:167], v222, s[22:23] offset:16
	global_load_dwordx4 v[168:171], v222, s[22:23] offset:2048
	global_load_dwordx4 v[172:175], v222, s[22:23] offset:2064
	global_load_dwordx4 v[224:227], v222, s[24:25]
	global_load_dwordx4 v[228:231], v222, s[24:25] offset:16
	global_load_dwordx4 v[232:235], v222, s[24:25] offset:2048
	global_load_dwordx4 v[236:239], v222, s[24:25] offset:2064

; __device__ __forceinline__ unsigned cvt_pk_bf16(float lo, float hi) { unsigned r; asm volatile("v_cvt_pk_bf16_f32 %0, %1, %2" : "=v"(r) : "v"(lo), "v"(hi)); return r; }
; __device__ __forceinline__ void epi_store(const f32x4 (&acc)[2][2][4][2], const Unit& u, int wr, int wc, int fr, int fq, const EpiP& e) {
;     ...
;                 const int row = row0 + ai * HALF + m * 16;
;                 f32x4 v0 = acc[ai][bj][m][0], v1 = acc[ai][bj][m][1];
;                 if (kind != 0 && row < MLAT) {
;                     const int t = row & (SEQ - 1); const int pos = (kind == 1) ? (t >> 6) : (t & 63);
;                     const f32x4 t0 = *(const f32x4*)(e.rope + (pos * 16 + 4 * fq) * 2), t1 = *(const f32x4*)(e.rope + (pos * 16 + 4 * fq) * 2 + 4);
;                     const float cs[4] = {t0[0], t0[2], t1[0], t1[2]}, sn[4] = {t0[1], t0[3], t1[1], t1[3]};
; #pragma unroll
;                     for (int j = 0; j < 4; ++j) { const float x1 = v0[j], x2 = v1[j]; v0[j] = x1 * cs[j] - x2 * sn[j]; v1[j] = x2 * cs[j] + x1 * sn[j]; }
;                 }
;                 bf16_t* rowp = e.O + (size_t)row * e.ldo + c;
;                 u32x2 w0, w1; w0.x = cvt_pk_bf16(v0[0], v0[1]); w0.y = cvt_pk_bf16(v0[2], v0[3]); w1.x = cvt_pk_bf16(v1[0], v1[1]); w1.y = cvt_pk_bf16(v1[2], v1[3]);
;                 const bool odd = (fq & 1) != 0;
;                 const unsigned sx = odd ? w0.x : w1.x, sy = odd ? w0.y : w1.y;
;                 const unsigned rx = (unsigned)__shfl_xor((int)sx, 16), ry = (unsigned)__shfl_xor((int)sy, 16);
;                 u32x4 w; if (odd) { w.x = rx; w.y = ry; w.z = w1.x; w.w = w1.y; } else { w.x = w0.x; w.y = w0.y; w.z = rx; w.w = ry; }
;                 *(u32x4*)(rowp + (odd ? 12 : 0)) = w;
.Lrp_loaded:
	s_cmp_eq_u32 s20, 0
	s_cbranch_scc1 .Lrp_plain0
	s_cmp_eq_u32 s20, 1
	s_cbranch_scc0 .Lrp_k2_0
	s_mov_b64 s[98:99], s[100:101]
	v_mul_f32_e32 v248, v124, v161
	v_mul_f32_e32 v249, v128, v161
	v_fma_f32 v240, v128, v160, -v248
	v_fma_f32 v244, v124, v160, v249
	v_mul_f32_e32 v248, v125, v163
	v_mul_f32_e32 v249, v129, v163
	v_fma_f32 v241, v129, v162, -v248
	v_fma_f32 v245, v125, v162, v249
	v_mul_f32_e32 v248, v126, v165
	v_mul_f32_e32 v249, v130, v165
	v_fma_f32 v242, v130, v164, -v248
	v_fma_f32 v246, v126, v164, v249
	v_mul_f32_e32 v248, v127, v167
	v_mul_f32_e32 v249, v131, v167
	v_fma_f32 v243, v131, v166, -v248
	v_fma_f32 v247, v127, v166, v249
	v_cvt_pk_bf16_f32 v204, v240, v241
	v_cvt_pk_bf16_f32 v205, v242, v243
	v_cvt_pk_bf16_f32 v206, v244, v245
	v_cvt_pk_bf16_f32 v207, v246, v247
	s_nop 1
	v_permlane16_swap_b32_e32 v204, v206
	v_permlane16_swap_b32_e32 v205, v207
	global_store_dwordx4 v216, v[204:207], s[98:99]
	s_mul_i32 s18, s19, 1
	s_add_u32 s98, s100, s18
	s_addc_u32 s99, s101, 0
	v_mul_f32_e32 v248, v116, v161
	v_mul_f32_e32 v249, v120, v161
	v_fma_f32 v240, v120, v160, -v248
	v_fma_f32 v244, v116, v160, v249
	v_mul_f32_e32 v248, v117, v163
	v_mul_f32_e32 v249, v121, v163
	v_fma_f32 v241, v121, v162, -v248
	v_fma_f32 v245, v117, v162, v249
	v_mul_f32_e32 v248, v118, v165
	v_mul_f32_e32 v249, v122, v165
	v_fma_f32 v242, v122, v164, -v248
	v_fma_f32 v246, v118, v164, v249
	v_mul_f32_e32 v248, v119, v167
	v_mul_f32_e32 v249, v123, v167
	v_fma_f32 v243, v123, v166, -v248
	v_fma_f32 v247, v119, v166, v249
	v_cvt_pk_bf16_f32 v132, v240, v241
	v_cvt_pk_bf16_f32 v133, v242, v243
	v_cvt_pk_bf16_f32 v134, v244, v245
	v_cvt_pk_bf16_f32 v135, v246, v247
	s_nop 1
	v_permlane16_swap_b32_e32 v132, v134
	v_permlane16_swap_b32_e32 v133, v135
	global_store_dwordx4 v216, v[132:135], s[98:99]
	s_mul_i32 s18, s19, 2
	s_add_u32 s98, s100, s18
	s_addc_u32 s99, s101, 0
	v_mul_f32_e32 v248, v108, v161
	v_mul_f32_e32 v249, v112, v161
	v_fma_f32 v240, v112, v160, -v248
	v_fma_f32 v244, v108, v160, v249
	v_mul_f32_e32 v248, v109, v163
	v_mul_f32_e32 v249, v113, v163
	v_fma_f32 v241, v113, v162, -v248
	v_fma_f32 v245, v109, v162, v249
	v_mul_f32_e32 v248, v110, v165
	v_mul_f32_e32 v249, v114, v165
	v_fma_f32 v242, v114, v164, -v248
	v_fma_f32 v246, v110, v164, v249
	v_mul_f32_e32 v248, v111, v167
	v_mul_f32_e32 v249, v115, v167
	v_fma_f32 v243, v115, v166, -v248
	v_fma_f32 v247, v111, v166, v249
	v_cvt_pk_bf16_f32 v136, v240, v241
	v_cvt_pk_bf16_f32 v137, v242, v243
	v_cvt_pk_bf16_f32 v138, v244, v245
	v_cvt_pk_bf16_f32 v139, v246, v247
	s_nop 1
	v_permlane16_swap_b32_e32 v136, v138
	v_permlane16_swap_b32_e32 v137, v139
	global_store_dwordx4 v216, v[136:139], s[98:99]
	s_mul_i32 s18, s19, 3
	s_add_u32 s98, s100, s18
	s_addc_u32 s99, s101, 0
	v_mul_f32_e32 v248, v100, v161
	v_mul_f32_e32 v249, v104, v161
	v_fma_f32 v240, v104, v160, -v248
	v_fma_f32 v244, v100, v160, v249
	v_mul_f32_e32 v248, v101, v163
	v_mul_f32_e32 v249, v105, v163
	v_fma_f32 v241, v105, v162, -v248
	v_fma_f32 v245, v101, v162, v249
	v_mul_f32_e32 v248, v102, v165
	v_mul_f32_e32 v249, v106, v165
	v_fma_f32 v242, v106, v164, -v248
	v_fma_f32 v246, v102, v164, v249
	v_mul_f32_e32 v248, v103, v167
	v_mul_f32_e32 v249, v107, v167
	v_fma_f32 v243, v107, v166, -v248
	v_fma_f32 v247, v103, v166, v249
	v_cvt_pk_bf16_f32 v204, v240, v241
	v_cvt_pk_bf16_f32 v205, v242, v243
	v_cvt_pk_bf16_f32 v206, v244, v245
	v_cvt_pk_bf16_f32 v207, v246, v247
	s_nop 1
	v_permlane16_swap_b32_e32 v204, v206
	v_permlane16_swap_b32_e32 v205, v207
	global_store_dwordx4 v216, v[204:207], s[98:99]
	s_mul_i32 s18, s19, 8
	s_add_u32 s98, s100, s18
	s_addc_u32 s99, s101, 0
	v_mul_f32_e32 v248, v56, v169
	v_mul_f32_e32 v249, v60, v169
	v_fma_f32 v240, v60, v168, -v248
	v_fma_f32 v244, v56, v168, v249
	v_mul_f32_e32 v248, v57, v171
	v_mul_f32_e32 v249, v61, v171
	v_fma_f32 v241, v61, v170, -v248
	v_fma_f32 v245, v57, v170, v249
	v_mul_f32_e32 v248, v58, v173
	v_mul_f32_e32 v249, v62, v173
	v_fma_f32 v242, v62, v172, -v248
	v_fma_f32 v246, v58, v172, v249
	v_mul_f32_e32 v248, v59, v175
	v_mul_f32_e32 v249, v63, v175
	v_fma_f32 v243, v63, v174, -v248
	v_fma_f32 v247, v59, v174, v249
	v_cvt_pk_bf16_f32 v132, v240, v241
	v_cvt_pk_bf16_f32 v133, v242, v243
	v_cvt_pk_bf16_f32 v134, v244, v245
	v_cvt_pk_bf16_f32 v135, v246, v247
	s_nop 1
	v_permlane16_swap_b32_e32 v132, v134
	v_permlane16_swap_b32_e32 v133, v135
	global_store_dwordx4 v216, v[132:135], s[98:99]
	s_mul_i32 s18, s19, 9
	s_add_u32 s98, s100, s18
	s_addc_u32 s99, s101, 0
	v_mul_f32_e32 v248, v48, v169
	v_mul_f32_e32 v249, v52, v169
	v_fma_f32 v240, v52, v168, -v248
	v_fma_f32 v244, v48, v168, v249
	v_mul_f32_e32 v248, v49, v171
	v_mul_f32_e32 v249, v53, v171
	v_fma_f32 v241, v53, v170, -v248
	v_fma_f32 v245, v49, v170, v249
	v_mul_f32_e32 v248, v50, v173
	v_mul_f32_e32 v249, v54, v173
	v_fma_f32 v242, v54, v172, -v248
	v_fma_f32 v246, v50, v172, v249
	v_mul_f32_e32 v248, v51, v175
	v_mul_f32_e32 v249, v55, v175
	v_fma_f32 v243, v55, v174, -v248
	v_fma_f32 v247, v51, v174, v249
	v_cvt_pk_bf16_f32 v136, v240, v241
	v_cvt_pk_bf16_f32 v137, v242, v243
	v_cvt_pk_bf16_f32 v138, v244, v245
	v_cvt_pk_bf16_f32 v139, v246, v247
	s_nop 1
	v_permlane16_swap_b32_e32 v136, v138
	v_permlane16_swap_b32_e32 v137, v139
	global_store_dwordx4 v216, v[136:139], s[98:99]
	s_mul_i32 s18, s19, 10
	s_add_u32 s98, s100, s18
	s_addc_u32 s99, s101, 0
	v_mul_f32_e32 v248, v40, v169
	v_mul_f32_e32 v249, v44, v169
	v_fma_f32 v240, v44, v168, -v248
	v_fma_f32 v244, v40, v168, v249
	v_mul_f32_e32 v248, v41, v171
	v_mul_f32_e32 v249, v45, v171
	v_fma_f32 v241, v45, v170, -v248
; __device__ __forceinline__ unsigned cvt_pk_bf16(float lo, float hi) { unsigned r; asm volatile("v_cvt_pk_bf16_f32 %0, %1, %2" : "=v"(r) : "v"(lo), "v"(hi)); return r; }
; __device__ __forceinline__ void epi_store(const f32x4 (&acc)[2][2][4][2], const Unit& u, int wr, int wc, int fr, int fq, const EpiP& e) {
;     ...
;                 const int row = row0 + ai * HALF + m * 16;
;                 f32x4 v0 = acc[ai][bj][m][0], v1 = acc[ai][bj][m][1];
;                 if (kind != 0 && row < MLAT) {
;                     const int t = row & (SEQ - 1); const int pos = (kind == 1) ? (t >> 6) : (t & 63);
;                     const f32x4 t0 = *(const f32x4*)(e.rope + (pos * 16 + 4 * fq) * 2), t1 = *(const f32x4*)(e.rope + (pos * 16 + 4 * fq) * 2 + 4);
;                     const float cs[4] = {t0[0], t0[2], t1[0], t1[2]}, sn[4] = {t0[1], t0[3], t1[1], t1[3]};
; #pragma unroll
;                     for (int j = 0; j < 4; ++j) { const float x1 = v0[j], x2 = v1[j]; v0[j] = x1 * cs[j] - x2 * sn[j]; v1[j] = x2 * cs[j] + x1 * sn[j]; }
;                 }
;                 bf16_t* rowp = e.O + (size_t)row * e.ldo + c;
;                 u32x2 w0, w1; w0.x = cvt_pk_bf16(v0[0], v0[1]); w0.y = cvt_pk_bf16(v0[2], v0[3]); w1.x = cvt_pk_bf16(v1[0], v1[1]); w1.y = cvt_pk_bf16(v1[2], v1[3]);
;                 const bool odd = (fq & 1) != 0;
;                 const unsigned sx = odd ? w0.x : w1.x, sy = odd ? w0.y : w1.y;
;                 const unsigned rx = (unsigned)__shfl_xor((int)sx, 16), ry = (unsigned)__shfl_xor((int)sy, 16);
;                 u32x4 w; if (odd) { w.x = rx; w.y = ry; w.z = w1.x; w.w = w1.y; } else { w.x = w0.x; w.y = w0.y; w.z = rx; w.w = ry; }
;                 *(u32x4*)(rowp + (odd ? 12 : 0)) = w;
	v_fma_f32 v245, v41, v170, v249
	v_mul_f32_e32 v248, v42, v173
	v_mul_f32_e32 v249, v46, v173
	v_fma_f32 v242, v46, v172, -v248
	v_fma_f32 v246, v42, v172, v249
	v_mul_f32_e32 v248, v43, v175
	v_mul_f32_e32 v249, v47, v175
	v_fma_f32 v243, v47, v174, -v248
	v_fma_f32 v247, v43, v174, v249
	v_cvt_pk_bf16_f32 v204, v240, v241
	v_cvt_pk_bf16_f32 v205, v242, v243
	v_cvt_pk_bf16_f32 v206, v244, v245
	v_cvt_pk_bf16_f32 v207, v246, v247
	s_nop 1
	v_permlane16_swap_b32_e32 v204, v206
	v_permlane16_swap_b32_e32 v205, v207
	global_store_dwordx4 v216, v[204:207], s[98:99]
	s_mul_i32 s18, s19, 11
	s_add_u32 s98, s100, s18
	s_addc_u32 s99, s101, 0
	v_mul_f32_e32 v248, v32, v169
	v_mul_f32_e32 v249, v36, v169
	v_fma_f32 v240, v36, v168, -v248
	v_fma_f32 v244, v32, v168, v249
	v_mul_f32_e32 v248, v33, v171
	v_mul_f32_e32 v249, v37, v171
	v_fma_f32 v241, v37, v170, -v248
	v_fma_f32 v245, v33, v170, v249
	v_mul_f32_e32 v248, v34, v173
	v_mul_f32_e32 v249, v38, v173
	v_fma_f32 v242, v38, v172, -v248
	v_fma_f32 v246, v34, v172, v249
	v_mul_f32_e32 v248, v35, v175
	v_mul_f32_e32 v249, v39, v175
	v_fma_f32 v243, v39, v174, -v248
	v_fma_f32 v247, v35, v174, v249
	v_cvt_pk_bf16_f32 v132, v240, v241
	v_cvt_pk_bf16_f32 v133, v242, v243
	v_cvt_pk_bf16_f32 v134, v244, v245
	v_cvt_pk_bf16_f32 v135, v246, v247
	s_nop 1
	v_permlane16_swap_b32_e32 v132, v134
	v_permlane16_swap_b32_e32 v133, v135
	global_store_dwordx4 v216, v[132:135], s[98:99]
	s_branch .Lrp_end0
.Lrp_k2_0:
	s_mov_b64 s[98:99], s[100:101]
	v_mul_f32_e32 v248, v124, v161
	v_mul_f32_e32 v249, v128, v161
	v_fma_f32 v240, v128, v160, -v248
	v_fma_f32 v244, v124, v160, v249
	v_mul_f32_e32 v248, v125, v163
	v_mul_f32_e32 v249, v129, v163
	v_fma_f32 v241, v129, v162, -v248
	v_fma_f32 v245, v125, v162, v249
	v_mul_f32_e32 v248, v126, v165
	v_mul_f32_e32 v249, v130, v165
	v_fma_f32 v242, v130, v164, -v248
	v_fma_f32 v246, v126, v164, v249
	v_mul_f32_e32 v248, v127, v167
	v_mul_f32_e32 v249, v131, v167
	v_fma_f32 v243, v131, v166, -v248
	v_fma_f32 v247, v127, v166, v249
	v_cvt_pk_bf16_f32 v136, v240, v241
	v_cvt_pk_bf16_f32 v137, v242, v243
	v_cvt_pk_bf16_f32 v138, v244, v245
	v_cvt_pk_bf16_f32 v139, v246, v247
	s_nop 1
	v_permlane16_swap_b32_e32 v136, v138
	v_permlane16_swap_b32_e32 v137, v139
	global_store_dwordx4 v216, v[136:139], s[98:99]
	s_mul_i32 s18, s19, 1
	s_add_u32 s98, s100, s18
	s_addc_u32 s99, s101, 0
	v_mul_f32_e32 v248, v116, v169
	v_mul_f32_e32 v249, v120, v169
	v_fma_f32 v240, v120, v168, -v248
	v_fma_f32 v244, v116, v168, v249
	v_mul_f32_e32 v248, v117, v171
	v_mul_f32_e32 v249, v121, v171
	v_fma_f32 v241, v121, v170, -v248
	v_fma_f32 v245, v117, v170, v249
	v_mul_f32_e32 v248, v118, v173
	v_mul_f32_e32 v249, v122, v173
	v_fma_f32 v242, v122, v172, -v248
	v_fma_f32 v246, v118, v172, v249
	v_mul_f32_e32 v248, v119, v175
	v_mul_f32_e32 v249, v123, v175
	v_fma_f32 v243, v123, v174, -v248
	v_fma_f32 v247, v119, v174, v249
	v_cvt_pk_bf16_f32 v204, v240, v241
	v_cvt_pk_bf16_f32 v205, v242, v243
	v_cvt_pk_bf16_f32 v206, v244, v245
	v_cvt_pk_bf16_f32 v207, v246, v247
	s_nop 1
	v_permlane16_swap_b32_e32 v204, v206
	v_permlane16_swap_b32_e32 v205, v207
	global_store_dwordx4 v216, v[204:207], s[98:99]
	s_mul_i32 s18, s19, 2
	s_add_u32 s98, s100, s18
	s_addc_u32 s99, s101, 0
	v_mul_f32_e32 v248, v108, v225
	v_mul_f32_e32 v249, v112, v225
	v_fma_f32 v240, v112, v224, -v248
	v_fma_f32 v244, v108, v224, v249
	v_mul_f32_e32 v248, v109, v227
	v_mul_f32_e32 v249, v113, v227
	v_fma_f32 v241, v113, v226, -v248
	v_fma_f32 v245, v109, v226, v249
	v_mul_f32_e32 v248, v110, v229
	v_mul_f32_e32 v249, v114, v229
	v_fma_f32 v242, v114, v228, -v248
	v_fma_f32 v246, v110, v228, v249
	v_mul_f32_e32 v248, v111, v231
	v_mul_f32_e32 v249, v115, v231
	v_fma_f32 v243, v115, v230, -v248
	v_fma_f32 v247, v111, v230, v249
	v_cvt_pk_bf16_f32 v132, v240, v241
	v_cvt_pk_bf16_f32 v133, v242, v243
	v_cvt_pk_bf16_f32 v134, v244, v245
	v_cvt_pk_bf16_f32 v135, v246, v247
	s_nop 1
	v_permlane16_swap_b32_e32 v132, v134
	v_permlane16_swap_b32_e32 v133, v135
	global_store_dwordx4 v216, v[132:135], s[98:99]
	s_mul_i32 s18, s19, 3
	s_add_u32 s98, s100, s18
	s_addc_u32 s99, s101, 0
	v_mul_f32_e32 v248, v100, v233
	v_mul_f32_e32 v249, v104, v233
	v_fma_f32 v240, v104, v232, -v248
	v_fma_f32 v244, v100, v232, v249
	v_mul_f32_e32 v248, v101, v235
	v_mul_f32_e32 v249, v105, v235
	v_fma_f32 v241, v105, v234, -v248
	v_fma_f32 v245, v101, v234, v249
	v_mul_f32_e32 v248, v102, v237
	v_mul_f32_e32 v249, v106, v237
	v_fma_f32 v242, v106, v236, -v248
	v_fma_f32 v246, v102, v236, v249
	v_mul_f32_e32 v248, v103, v239
	v_mul_f32_e32 v249, v107, v239
	v_fma_f32 v243, v107, v238, -v248
	v_fma_f32 v247, v103, v238, v249
	v_cvt_pk_bf16_f32 v136, v240, v241
	v_cvt_pk_bf16_f32 v137, v242, v243
	v_cvt_pk_bf16_f32 v138, v244, v245
	v_cvt_pk_bf16_f32 v139, v246, v247
	s_nop 1
	v_permlane16_swap_b32_e32 v136, v138
	v_permlane16_swap_b32_e32 v137, v139
	global_store_dwordx4 v216, v[136:139], s[98:99]
	s_mul_i32 s18, s19, 8
	s_add_u32 s98, s100, s18
	s_addc_u32 s99, s101, 0
	v_mul_f32_e32 v248, v56, v161
	v_mul_f32_e32 v249, v60, v161
	v_fma_f32 v240, v60, v160, -v248
	v_fma_f32 v244, v56, v160, v249
	v_mul_f32_e32 v248, v57, v163
	v_mul_f32_e32 v249, v61, v163
	v_fma_f32 v241, v61, v162, -v248
	v_fma_f32 v245, v57, v162, v249
	v_mul_f32_e32 v248, v58, v165
	v_mul_f32_e32 v249, v62, v165
	v_fma_f32 v242, v62, v164, -v248
	v_fma_f32 v246, v58, v164, v249
	v_mul_f32_e32 v248, v59, v167
	v_mul_f32_e32 v249, v63, v167
	v_fma_f32 v243, v63, v166, -v248
	v_fma_f32 v247, v59, v166, v249
	v_cvt_pk_bf16_f32 v204, v240, v241
	v_cvt_pk_bf16_f32 v205, v242, v243
; __device__ __forceinline__ unsigned cvt_pk_bf16(float lo, float hi) { unsigned r; asm volatile("v_cvt_pk_bf16_f32 %0, %1, %2" : "=v"(r) : "v"(lo), "v"(hi)); return r; }
; __device__ __forceinline__ void epi_store(const f32x4 (&acc)[2][2][4][2], const Unit& u, int wr, int wc, int fr, int fq, const EpiP& e) {
;     ...
;                 bf16_t* rowp = e.O + (size_t)row * e.ldo + c;
;                 u32x2 w0, w1; w0.x = cvt_pk_bf16(v0[0], v0[1]); w0.y = cvt_pk_bf16(v0[2], v0[3]); w1.x = cvt_pk_bf16(v1[0], v1[1]); w1.y = cvt_pk_bf16(v1[2], v1[3]);
;                 const bool odd = (fq & 1) != 0;
;                 const unsigned sx = odd ? w0.x : w1.x, sy = odd ? w0.y : w1.y;
;                 const unsigned rx = (unsigned)__shfl_xor((int)sx, 16), ry = (unsigned)__shfl_xor((int)sy, 16);
;                 u32x4 w; if (odd) { w.x = rx; w.y = ry; w.z = w1.x; w.w = w1.y; } else { w.x = w0.x; w.y = w0.y; w.z = rx; w.w = ry; }
;                 *(u32x4*)(rowp + (odd ? 12 : 0)) = w;
	v_cvt_pk_bf16_f32 v206, v244, v245
	v_cvt_pk_bf16_f32 v207, v246, v247
	s_nop 1
	v_permlane16_swap_b32_e32 v204, v206
	v_permlane16_swap_b32_e32 v205, v207
	global_store_dwordx4 v216, v[204:207], s[98:99]
	s_mul_i32 s18, s19, 9
	s_add_u32 s98, s100, s18
	s_addc_u32 s99, s101, 0
	v_mul_f32_e32 v248, v48, v169
	v_mul_f32_e32 v249, v52, v169
	v_fma_f32 v240, v52, v168, -v248
	v_fma_f32 v244, v48, v168, v249
	v_mul_f32_e32 v248, v49, v171
	v_mul_f32_e32 v249, v53, v171
	v_fma_f32 v241, v53, v170, -v248
	v_fma_f32 v245, v49, v170, v249
	v_mul_f32_e32 v248, v50, v173
	v_mul_f32_e32 v249, v54, v173
	v_fma_f32 v242, v54, v172, -v248
	v_fma_f32 v246, v50, v172, v249
	v_mul_f32_e32 v248, v51, v175
	v_mul_f32_e32 v249, v55, v175
	v_fma_f32 v243, v55, v174, -v248
	v_fma_f32 v247, v51, v174, v249
	v_cvt_pk_bf16_f32 v132, v240, v241
	v_cvt_pk_bf16_f32 v133, v242, v243
	v_cvt_pk_bf16_f32 v134, v244, v245
	v_cvt_pk_bf16_f32 v135, v246, v247
	s_nop 1
	v_permlane16_swap_b32_e32 v132, v134
	v_permlane16_swap_b32_e32 v133, v135
	global_store_dwordx4 v216, v[132:135], s[98:99]
	s_mul_i32 s18, s19, 10
	s_add_u32 s98, s100, s18
	s_addc_u32 s99, s101, 0
	v_mul_f32_e32 v248, v40, v225
	v_mul_f32_e32 v249, v44, v225
	v_fma_f32 v240, v44, v224, -v248
	v_fma_f32 v244, v40, v224, v249
	v_mul_f32_e32 v248, v41, v227
	v_mul_f32_e32 v249, v45, v227
	v_fma_f32 v241, v45, v226, -v248
	v_fma_f32 v245, v41, v226, v249
	v_mul_f32_e32 v248, v42, v229
	v_mul_f32_e32 v249, v46, v229
	v_fma_f32 v242, v46, v228, -v248
	v_fma_f32 v246, v42, v228, v249
	v_mul_f32_e32 v248, v43, v231
	v_mul_f32_e32 v249, v47, v231
	v_fma_f32 v243, v47, v230, -v248
	v_fma_f32 v247, v43, v230, v249
	v_cvt_pk_bf16_f32 v136, v240, v241
	v_cvt_pk_bf16_f32 v137, v242, v243
	v_cvt_pk_bf16_f32 v138, v244, v245
	v_cvt_pk_bf16_f32 v139, v246, v247
	s_nop 1
	v_permlane16_swap_b32_e32 v136, v138
	v_permlane16_swap_b32_e32 v137, v139
	global_store_dwordx4 v216, v[136:139], s[98:99]
	s_mul_i32 s18, s19, 11
	s_add_u32 s98, s100, s18
	s_addc_u32 s99, s101, 0
	v_mul_f32_e32 v248, v32, v233
	v_mul_f32_e32 v249, v36, v233
	v_fma_f32 v240, v36, v232, -v248
	v_fma_f32 v244, v32, v232, v249
	v_mul_f32_e32 v248, v33, v235
	v_mul_f32_e32 v249, v37, v235
	v_fma_f32 v241, v37, v234, -v248
	v_fma_f32 v245, v33, v234, v249
	v_mul_f32_e32 v248, v34, v237
	v_mul_f32_e32 v249, v38, v237
	v_fma_f32 v242, v38, v236, -v248
	v_fma_f32 v246, v34, v236, v249
	v_mul_f32_e32 v248, v35, v239
	v_mul_f32_e32 v249, v39, v239
	v_fma_f32 v243, v39, v238, -v248
	v_fma_f32 v247, v35, v238, v249
	v_cvt_pk_bf16_f32 v204, v240, v241
	v_cvt_pk_bf16_f32 v205, v242, v243
	v_cvt_pk_bf16_f32 v206, v244, v245
	v_cvt_pk_bf16_f32 v207, v246, v247
	s_nop 1
	v_permlane16_swap_b32_e32 v204, v206
	v_permlane16_swap_b32_e32 v205, v207
	global_store_dwordx4 v216, v[204:207], s[98:99]
	s_branch .Lrp_end0
.Lrp_plain0:
	s_mov_b64 s[98:99], s[100:101]
	v_cvt_pk_bf16_f32 v132, v128, v129
	v_cvt_pk_bf16_f32 v133, v130, v131
	v_cvt_pk_bf16_f32 v134, v124, v125
	v_cvt_pk_bf16_f32 v135, v126, v127
	s_nop 1
	v_permlane16_swap_b32_e32 v132, v134
	v_permlane16_swap_b32_e32 v133, v135
	global_store_dwordx4 v216, v[132:135], s[98:99]
	s_mul_i32 s18, s19, 1
	s_add_u32 s98, s100, s18
	s_addc_u32 s99, s101, 0
	v_cvt_pk_bf16_f32 v136, v120, v121
	v_cvt_pk_bf16_f32 v137, v122, v123
	v_cvt_pk_bf16_f32 v138, v116, v117
	v_cvt_pk_bf16_f32 v139, v118, v119
	s_nop 1
	v_permlane16_swap_b32_e32 v136, v138
	v_permlane16_swap_b32_e32 v137, v139
	global_store_dwordx4 v216, v[136:139], s[98:99]
	s_mul_i32 s18, s19, 2
	s_add_u32 s98, s100, s18
	s_addc_u32 s99, s101, 0
	v_cvt_pk_bf16_f32 v204, v112, v113
	v_cvt_pk_bf16_f32 v205, v114, v115
	v_cvt_pk_bf16_f32 v206, v108, v109
	v_cvt_pk_bf16_f32 v207, v110, v111
	s_nop 1
	v_permlane16_swap_b32_e32 v204, v206
	v_permlane16_swap_b32_e32 v205, v207
	global_store_dwordx4 v216, v[204:207], s[98:99]
	s_mul_i32 s18, s19, 3
	s_add_u32 s98, s100, s18
	s_addc_u32 s99, s101, 0
	v_cvt_pk_bf16_f32 v132, v104, v105
	v_cvt_pk_bf16_f32 v133, v106, v107
	v_cvt_pk_bf16_f32 v134, v100, v101
	v_cvt_pk_bf16_f32 v135, v102, v103
	s_nop 1
	v_permlane16_swap_b32_e32 v132, v134
	v_permlane16_swap_b32_e32 v133, v135
	global_store_dwordx4 v216, v[132:135], s[98:99]
	s_mul_i32 s18, s19, 8
	s_add_u32 s98, s100, s18
	s_addc_u32 s99, s101, 0
	v_cvt_pk_bf16_f32 v136, v60, v61
	v_cvt_pk_bf16_f32 v137, v62, v63
	v_cvt_pk_bf16_f32 v138, v56, v57
	v_cvt_pk_bf16_f32 v139, v58, v59
	s_nop 1
	v_permlane16_swap_b32_e32 v136, v138
	v_permlane16_swap_b32_e32 v137, v139
	global_store_dwordx4 v216, v[136:139], s[98:99]
	s_mul_i32 s18, s19, 9
	s_add_u32 s98, s100, s18
	s_addc_u32 s99, s101, 0
	v_cvt_pk_bf16_f32 v204, v52, v53
	v_cvt_pk_bf16_f32 v205, v54, v55
	v_cvt_pk_bf16_f32 v206, v48, v49
	v_cvt_pk_bf16_f32 v207, v50, v51
	s_nop 1
	v_permlane16_swap_b32_e32 v204, v206
	v_permlane16_swap_b32_e32 v205, v207
	global_store_dwordx4 v216, v[204:207], s[98:99]
	s_mul_i32 s18, s19, 10
	s_add_u32 s98, s100, s18
	s_addc_u32 s99, s101, 0
	v_cvt_pk_bf16_f32 v132, v44, v45
	v_cvt_pk_bf16_f32 v133, v46, v47
	v_cvt_pk_bf16_f32 v134, v40, v41
	v_cvt_pk_bf16_f32 v135, v42, v43
	s_nop 1
	v_permlane16_swap_b32_e32 v132, v134
	v_permlane16_swap_b32_e32 v133, v135
	global_store_dwordx4 v216, v[132:135], s[98:99]
	s_mul_i32 s18, s19, 11
	s_add_u32 s98, s100, s18
	s_addc_u32 s99, s101, 0
	v_cvt_pk_bf16_f32 v136, v36, v37
	v_cvt_pk_bf16_f32 v137, v38, v39
	v_cvt_pk_bf16_f32 v138, v32, v33
	v_cvt_pk_bf16_f32 v139, v34, v35
	s_nop 1
	v_permlane16_swap_b32_e32 v136, v138
	v_permlane16_swap_b32_e32 v137, v139
	global_store_dwordx4 v216, v[136:139], s[98:99]
; __device__ __forceinline__ unsigned cvt_pk_bf16(float lo, float hi) { unsigned r; asm volatile("v_cvt_pk_bf16_f32 %0, %1, %2" : "=v"(r) : "v"(lo), "v"(hi)); return r; }
; __device__ __forceinline__ void epi_store(const f32x4 (&acc)[2][2][4][2], const Unit& u, int wr, int wc, int fr, int fq, const EpiP& e) {
;     ...
;     for (int bj = 0; bj < 2; ++bj) {
;         const int c = col0 + bj * HALF;
;         int kind = 0;
;         if (e.mode == 2) { if (c < 2048) kind = ((c >> 5) & 1) ? 2 : 1; }
;         else { const int d = c % 192; if (d >= 128) kind = (d >= 160) ? 2 : 1; }
; #pragma unroll
;         for (int ai = 0; ai < 2; ++ai)
; #pragma unroll
;             for (int m = 0; m < 4; ++m) {
;                 const int row = row0 + ai * HALF + m * 16;
;                 f32x4 v0 = acc[ai][bj][m][0], v1 = acc[ai][bj][m][1];
;                 if (kind != 0 && row < MLAT) {
;                     const int t = row & (SEQ - 1); const int pos = (kind == 1) ? (t >> 6) : (t & 63);
;                     const f32x4 t0 = *(const f32x4*)(e.rope + (pos * 16 + 4 * fq) * 2), t1 = *(const f32x4*)(e.rope + (pos * 16 + 4 * fq) * 2 + 4);
;                     const float cs[4] = {t0[0], t0[2], t1[0], t1[2]}, sn[4] = {t0[1], t0[3], t1[1], t1[3]};
; #pragma unroll
;                     for (int j = 0; j < 4; ++j) { const float x1 = v0[j], x2 = v1[j]; v0[j] = x1 * cs[j] - x2 * sn[j]; v1[j] = x2 * cs[j] + x1 * sn[j]; }
;                 }
;                 bf16_t* rowp = e.O + (size_t)row * e.ldo + c;
;                 u32x2 w0, w1; w0.x = cvt_pk_bf16(v0[0], v0[1]); w0.y = cvt_pk_bf16(v0[2], v0[3]); w1.x = cvt_pk_bf16(v1[0], v1[1]); w1.y = cvt_pk_bf16(v1[2], v1[3]);
;                 const bool odd = (fq & 1) != 0;
;                 const unsigned sx = odd ? w0.x : w1.x, sy = odd ? w0.y : w1.y;
;                 const unsigned rx = (unsigned)__shfl_xor((int)sx, 16), ry = (unsigned)__shfl_xor((int)sy, 16);
;                 u32x4 w; if (odd) { w.x = rx; w.y = ry; w.z = w1.x; w.w = w1.y; } else { w.x = w0.x; w.y = w0.y; w.z = rx; w.w = ry; }
;                 *(u32x4*)(rowp + (odd ? 12 : 0)) = w;
.Lrp_end0:
	s_cmp_eq_u32 s21, 0
	s_cbranch_scc1 .Lrp_plain1
	s_cmp_eq_u32 s21, 1
	s_cbranch_scc0 .Lrp_k2_1
	s_mov_b64 s[98:99], s[100:101]
	v_mul_f32_e32 v248, v88, v161
	v_mul_f32_e32 v249, v92, v161
	v_fma_f32 v240, v92, v160, -v248
	v_fma_f32 v244, v88, v160, v249
	v_mul_f32_e32 v248, v89, v163
	v_mul_f32_e32 v249, v93, v163
	v_fma_f32 v241, v93, v162, -v248
	v_fma_f32 v245, v89, v162, v249
	v_mul_f32_e32 v248, v90, v165
	v_mul_f32_e32 v249, v94, v165
	v_fma_f32 v242, v94, v164, -v248
	v_fma_f32 v246, v90, v164, v249
	v_mul_f32_e32 v248, v91, v167
	v_mul_f32_e32 v249, v95, v167
	v_fma_f32 v243, v95, v166, -v248
	v_fma_f32 v247, v91, v166, v249
	v_cvt_pk_bf16_f32 v204, v240, v241
	v_cvt_pk_bf16_f32 v205, v242, v243
	v_cvt_pk_bf16_f32 v206, v244, v245
	v_cvt_pk_bf16_f32 v207, v246, v247
	s_nop 1
	v_permlane16_swap_b32_e32 v204, v206
	v_permlane16_swap_b32_e32 v205, v207
	global_store_dwordx4 v216, v[204:207], s[98:99] offset:256
	s_mul_i32 s18, s19, 1
	s_add_u32 s98, s100, s18
	s_addc_u32 s99, s101, 0
	v_mul_f32_e32 v248, v80, v161
	v_mul_f32_e32 v249, v84, v161
	v_fma_f32 v240, v84, v160, -v248
	v_fma_f32 v244, v80, v160, v249
	v_mul_f32_e32 v248, v81, v163
	v_mul_f32_e32 v249, v85, v163
	v_fma_f32 v241, v85, v162, -v248
	v_fma_f32 v245, v81, v162, v249
	v_mul_f32_e32 v248, v82, v165
	v_mul_f32_e32 v249, v86, v165
	v_fma_f32 v242, v86, v164, -v248
	v_fma_f32 v246, v82, v164, v249
	v_mul_f32_e32 v248, v83, v167
	v_mul_f32_e32 v249, v87, v167
	v_fma_f32 v243, v87, v166, -v248
	v_fma_f32 v247, v83, v166, v249
	v_cvt_pk_bf16_f32 v132, v240, v241
	v_cvt_pk_bf16_f32 v133, v242, v243
	v_cvt_pk_bf16_f32 v134, v244, v245
	v_cvt_pk_bf16_f32 v135, v246, v247
	s_nop 1
	v_permlane16_swap_b32_e32 v132, v134
	v_permlane16_swap_b32_e32 v133, v135
	global_store_dwordx4 v216, v[132:135], s[98:99] offset:256
	s_mul_i32 s18, s19, 2
	s_add_u32 s98, s100, s18
	s_addc_u32 s99, s101, 0
	v_mul_f32_e32 v248, v72, v161
	v_mul_f32_e32 v249, v76, v161
	v_fma_f32 v240, v76, v160, -v248
	v_fma_f32 v244, v72, v160, v249
	v_mul_f32_e32 v248, v73, v163
	v_mul_f32_e32 v249, v77, v163
	v_fma_f32 v241, v77, v162, -v248
	v_fma_f32 v245, v73, v162, v249
	v_mul_f32_e32 v248, v74, v165
	v_mul_f32_e32 v249, v78, v165
	v_fma_f32 v242, v78, v164, -v248
	v_fma_f32 v246, v74, v164, v249
	v_mul_f32_e32 v248, v75, v167
	v_mul_f32_e32 v249, v79, v167
	v_fma_f32 v243, v79, v166, -v248
	v_fma_f32 v247, v75, v166, v249
	v_cvt_pk_bf16_f32 v136, v240, v241
	v_cvt_pk_bf16_f32 v137, v242, v243
	v_cvt_pk_bf16_f32 v138, v244, v245
	v_cvt_pk_bf16_f32 v139, v246, v247
	s_nop 1
	v_permlane16_swap_b32_e32 v136, v138
	v_permlane16_swap_b32_e32 v137, v139
	global_store_dwordx4 v216, v[136:139], s[98:99] offset:256
	s_mul_i32 s18, s19, 3
	s_add_u32 s98, s100, s18
	s_addc_u32 s99, s101, 0
	v_mul_f32_e32 v248, v64, v161
	v_mul_f32_e32 v249, v68, v161
	v_fma_f32 v240, v68, v160, -v248
	v_fma_f32 v244, v64, v160, v249
	v_mul_f32_e32 v248, v65, v163
	v_mul_f32_e32 v249, v69, v163
	v_fma_f32 v241, v69, v162, -v248
	v_fma_f32 v245, v65, v162, v249
	v_mul_f32_e32 v248, v66, v165
	v_mul_f32_e32 v249, v70, v165
	v_fma_f32 v242, v70, v164, -v248
	v_fma_f32 v246, v66, v164, v249
	v_mul_f32_e32 v248, v67, v167
	v_mul_f32_e32 v249, v71, v167
	v_fma_f32 v243, v71, v166, -v248
	v_fma_f32 v247, v67, v166, v249
	v_cvt_pk_bf16_f32 v204, v240, v241
	v_cvt_pk_bf16_f32 v205, v242, v243
	v_cvt_pk_bf16_f32 v206, v244, v245
	v_cvt_pk_bf16_f32 v207, v246, v247
	s_nop 1
	v_permlane16_swap_b32_e32 v204, v206
	v_permlane16_swap_b32_e32 v205, v207
	global_store_dwordx4 v216, v[204:207], s[98:99] offset:256
	s_mul_i32 s18, s19, 8
	s_add_u32 s98, s100, s18
	s_addc_u32 s99, s101, 0
	v_mul_f32_e32 v248, v24, v169
	v_mul_f32_e32 v249, v28, v169
	v_fma_f32 v240, v28, v168, -v248
	v_fma_f32 v244, v24, v168, v249
	v_mul_f32_e32 v248, v25, v171
	v_mul_f32_e32 v249, v29, v171
	v_fma_f32 v241, v29, v170, -v248
	v_fma_f32 v245, v25, v170, v249
	v_mul_f32_e32 v248, v26, v173
	v_mul_f32_e32 v249, v30, v173
	v_fma_f32 v242, v30, v172, -v248
	v_fma_f32 v246, v26, v172, v249
	v_mul_f32_e32 v248, v27, v175
	v_mul_f32_e32 v249, v31, v175
	v_fma_f32 v243, v31, v174, -v248
	v_fma_f32 v247, v27, v174, v249
	v_cvt_pk_bf16_f32 v132, v240, v241
	v_cvt_pk_bf16_f32 v133, v242, v243
	v_cvt_pk_bf16_f32 v134, v244, v245
	v_cvt_pk_bf16_f32 v135, v246, v247
	s_nop 1
	v_permlane16_swap_b32_e32 v132, v134
	v_permlane16_swap_b32_e32 v133, v135
	global_store_dwordx4 v216, v[132:135], s[98:99] offset:256
	s_mul_i32 s18, s19, 9
	s_add_u32 s98, s100, s18
	s_addc_u32 s99, s101, 0
	v_mul_f32_e32 v248, v16, v169
	v_mul_f32_e32 v249, v20, v169
	v_fma_f32 v240, v20, v168, -v248
	v_fma_f32 v244, v16, v168, v249
	v_mul_f32_e32 v248, v17, v171
	v_mul_f32_e32 v249, v21, v171
	v_fma_f32 v241, v21, v170, -v248
	v_fma_f32 v245, v17, v170, v249
	v_mul_f32_e32 v248, v18, v173
	v_mul_f32_e32 v249, v22, v173
	v_fma_f32 v242, v22, v172, -v248
	v_fma_f32 v246, v18, v172, v249
	v_mul_f32_e32 v248, v19, v175
	v_mul_f32_e32 v249, v23, v175
	v_fma_f32 v243, v23, v174, -v248
	v_fma_f32 v247, v19, v174, v249
	v_cvt_pk_bf16_f32 v136, v240, v241
	v_cvt_pk_bf16_f32 v137, v242, v243
	v_cvt_pk_bf16_f32 v138, v244, v245
	v_cvt_pk_bf16_f32 v139, v246, v247
	s_nop 1
	v_permlane16_swap_b32_e32 v136, v138
	v_permlane16_swap_b32_e32 v137, v139
	global_store_dwordx4 v216, v[136:139], s[98:99] offset:256
	s_mul_i32 s18, s19, 10
	s_add_u32 s98, s100, s18
	s_addc_u32 s99, s101, 0
	v_mul_f32_e32 v248, v8, v169
	v_mul_f32_e32 v249, v12, v169
	v_fma_f32 v240, v12, v168, -v248
	v_fma_f32 v244, v8, v168, v249
	v_mul_f32_e32 v248, v9, v171
	v_mul_f32_e32 v249, v13, v171
	v_fma_f32 v241, v13, v170, -v248
; __device__ __forceinline__ unsigned cvt_pk_bf16(float lo, float hi) { unsigned r; asm volatile("v_cvt_pk_bf16_f32 %0, %1, %2" : "=v"(r) : "v"(lo), "v"(hi)); return r; }
; __device__ __forceinline__ void epi_store(const f32x4 (&acc)[2][2][4][2], const Unit& u, int wr, int wc, int fr, int fq, const EpiP& e) {
;     ...
;                 const int row = row0 + ai * HALF + m * 16;
;                 f32x4 v0 = acc[ai][bj][m][0], v1 = acc[ai][bj][m][1];
;                 if (kind != 0 && row < MLAT) {
;                     const int t = row & (SEQ - 1); const int pos = (kind == 1) ? (t >> 6) : (t & 63);
;                     const f32x4 t0 = *(const f32x4*)(e.rope + (pos * 16 + 4 * fq) * 2), t1 = *(const f32x4*)(e.rope + (pos * 16 + 4 * fq) * 2 + 4);
;                     const float cs[4] = {t0[0], t0[2], t1[0], t1[2]}, sn[4] = {t0[1], t0[3], t1[1], t1[3]};
; #pragma unroll
;                     for (int j = 0; j < 4; ++j) { const float x1 = v0[j], x2 = v1[j]; v0[j] = x1 * cs[j] - x2 * sn[j]; v1[j] = x2 * cs[j] + x1 * sn[j]; }
;                 }
;                 bf16_t* rowp = e.O + (size_t)row * e.ldo + c;
;                 u32x2 w0, w1; w0.x = cvt_pk_bf16(v0[0], v0[1]); w0.y = cvt_pk_bf16(v0[2], v0[3]); w1.x = cvt_pk_bf16(v1[0], v1[1]); w1.y = cvt_pk_bf16(v1[2], v1[3]);
;                 const bool odd = (fq & 1) != 0;
;                 const unsigned sx = odd ? w0.x : w1.x, sy = odd ? w0.y : w1.y;
;                 const unsigned rx = (unsigned)__shfl_xor((int)sx, 16), ry = (unsigned)__shfl_xor((int)sy, 16);
;                 u32x4 w; if (odd) { w.x = rx; w.y = ry; w.z = w1.x; w.w = w1.y; } else { w.x = w0.x; w.y = w0.y; w.z = rx; w.w = ry; }
;                 *(u32x4*)(rowp + (odd ? 12 : 0)) = w;
	v_fma_f32 v245, v9, v170, v249
	v_mul_f32_e32 v248, v10, v173
	v_mul_f32_e32 v249, v14, v173
	v_fma_f32 v242, v14, v172, -v248
	v_fma_f32 v246, v10, v172, v249
	v_mul_f32_e32 v248, v11, v175
	v_mul_f32_e32 v249, v15, v175
	v_fma_f32 v243, v15, v174, -v248
	v_fma_f32 v247, v11, v174, v249
	v_cvt_pk_bf16_f32 v204, v240, v241
	v_cvt_pk_bf16_f32 v205, v242, v243
	v_cvt_pk_bf16_f32 v206, v244, v245
	v_cvt_pk_bf16_f32 v207, v246, v247
	s_nop 1
	v_permlane16_swap_b32_e32 v204, v206
	v_permlane16_swap_b32_e32 v205, v207
	global_store_dwordx4 v216, v[204:207], s[98:99] offset:256
	s_mul_i32 s18, s19, 11
	s_add_u32 s98, s100, s18
	s_addc_u32 s99, s101, 0
	v_mul_f32_e32 v248, v0, v169
	v_mul_f32_e32 v249, v4, v169
	v_fma_f32 v240, v4, v168, -v248
	v_fma_f32 v244, v0, v168, v249
	v_mul_f32_e32 v248, v1, v171
	v_mul_f32_e32 v249, v5, v171
	v_fma_f32 v241, v5, v170, -v248
	v_fma_f32 v245, v1, v170, v249
	v_mul_f32_e32 v248, v2, v173
	v_mul_f32_e32 v249, v6, v173
	v_fma_f32 v242, v6, v172, -v248
	v_fma_f32 v246, v2, v172, v249
	v_mul_f32_e32 v248, v3, v175
	v_mul_f32_e32 v249, v7, v175
	v_fma_f32 v243, v7, v174, -v248
	v_fma_f32 v247, v3, v174, v249
	v_cvt_pk_bf16_f32 v132, v240, v241
	v_cvt_pk_bf16_f32 v133, v242, v243
	v_cvt_pk_bf16_f32 v134, v244, v245
	v_cvt_pk_bf16_f32 v135, v246, v247
	s_nop 1
	v_permlane16_swap_b32_e32 v132, v134
	v_permlane16_swap_b32_e32 v133, v135
	global_store_dwordx4 v216, v[132:135], s[98:99] offset:256
	s_branch .Lrp_end1
.Lrp_k2_1:
	s_mov_b64 s[98:99], s[100:101]
	v_mul_f32_e32 v248, v88, v161
	v_mul_f32_e32 v249, v92, v161
	v_fma_f32 v240, v92, v160, -v248
	v_fma_f32 v244, v88, v160, v249
	v_mul_f32_e32 v248, v89, v163
	v_mul_f32_e32 v249, v93, v163
	v_fma_f32 v241, v93, v162, -v248
	v_fma_f32 v245, v89, v162, v249
	v_mul_f32_e32 v248, v90, v165
	v_mul_f32_e32 v249, v94, v165
	v_fma_f32 v242, v94, v164, -v248
	v_fma_f32 v246, v90, v164, v249
	v_mul_f32_e32 v248, v91, v167
	v_mul_f32_e32 v249, v95, v167
	v_fma_f32 v243, v95, v166, -v248
	v_fma_f32 v247, v91, v166, v249
	v_cvt_pk_bf16_f32 v136, v240, v241
	v_cvt_pk_bf16_f32 v137, v242, v243
	v_cvt_pk_bf16_f32 v138, v244, v245
	v_cvt_pk_bf16_f32 v139, v246, v247
	s_nop 1
	v_permlane16_swap_b32_e32 v136, v138
	v_permlane16_swap_b32_e32 v137, v139
	global_store_dwordx4 v216, v[136:139], s[98:99] offset:256
	s_mul_i32 s18, s19, 1
	s_add_u32 s98, s100, s18
	s_addc_u32 s99, s101, 0
	v_mul_f32_e32 v248, v80, v169
	v_mul_f32_e32 v249, v84, v169
	v_fma_f32 v240, v84, v168, -v248
	v_fma_f32 v244, v80, v168, v249
	v_mul_f32_e32 v248, v81, v171
	v_mul_f32_e32 v249, v85, v171
	v_fma_f32 v241, v85, v170, -v248
	v_fma_f32 v245, v81, v170, v249
	v_mul_f32_e32 v248, v82, v173
	v_mul_f32_e32 v249, v86, v173
	v_fma_f32 v242, v86, v172, -v248
	v_fma_f32 v246, v82, v172, v249
	v_mul_f32_e32 v248, v83, v175
	v_mul_f32_e32 v249, v87, v175
	v_fma_f32 v243, v87, v174, -v248
	v_fma_f32 v247, v83, v174, v249
	v_cvt_pk_bf16_f32 v204, v240, v241
	v_cvt_pk_bf16_f32 v205, v242, v243
	v_cvt_pk_bf16_f32 v206, v244, v245
	v_cvt_pk_bf16_f32 v207, v246, v247
	s_nop 1
	v_permlane16_swap_b32_e32 v204, v206
	v_permlane16_swap_b32_e32 v205, v207
	global_store_dwordx4 v216, v[204:207], s[98:99] offset:256
	s_mul_i32 s18, s19, 2
	s_add_u32 s98, s100, s18
	s_addc_u32 s99, s101, 0
	v_mul_f32_e32 v248, v72, v225
	v_mul_f32_e32 v249, v76, v225
	v_fma_f32 v240, v76, v224, -v248
	v_fma_f32 v244, v72, v224, v249
	v_mul_f32_e32 v248, v73, v227
	v_mul_f32_e32 v249, v77, v227
	v_fma_f32 v241, v77, v226, -v248
	v_fma_f32 v245, v73, v226, v249
	v_mul_f32_e32 v248, v74, v229
	v_mul_f32_e32 v249, v78, v229
	v_fma_f32 v242, v78, v228, -v248
	v_fma_f32 v246, v74, v228, v249
	v_mul_f32_e32 v248, v75, v231
	v_mul_f32_e32 v249, v79, v231
	v_fma_f32 v243, v79, v230, -v248
	v_fma_f32 v247, v75, v230, v249
	v_cvt_pk_bf16_f32 v132, v240, v241
	v_cvt_pk_bf16_f32 v133, v242, v243
	v_cvt_pk_bf16_f32 v134, v244, v245
	v_cvt_pk_bf16_f32 v135, v246, v247
	s_nop 1
	v_permlane16_swap_b32_e32 v132, v134
	v_permlane16_swap_b32_e32 v133, v135
	global_store_dwordx4 v216, v[132:135], s[98:99] offset:256
	s_mul_i32 s18, s19, 3
	s_add_u32 s98, s100, s18
	s_addc_u32 s99, s101, 0
	v_mul_f32_e32 v248, v64, v233
	v_mul_f32_e32 v249, v68, v233
	v_fma_f32 v240, v68, v232, -v248
	v_fma_f32 v244, v64, v232, v249
	v_mul_f32_e32 v248, v65, v235
	v_mul_f32_e32 v249, v69, v235
	v_fma_f32 v241, v69, v234, -v248
	v_fma_f32 v245, v65, v234, v249
	v_mul_f32_e32 v248, v66, v237
	v_mul_f32_e32 v249, v70, v237
	v_fma_f32 v242, v70, v236, -v248
	v_fma_f32 v246, v66, v236, v249
	v_mul_f32_e32 v248, v67, v239
	v_mul_f32_e32 v249, v71, v239
	v_fma_f32 v243, v71, v238, -v248
	v_fma_f32 v247, v67, v238, v249
	v_cvt_pk_bf16_f32 v136, v240, v241
	v_cvt_pk_bf16_f32 v137, v242, v243
	v_cvt_pk_bf16_f32 v138, v244, v245
	v_cvt_pk_bf16_f32 v139, v246, v247
	s_nop 1
	v_permlane16_swap_b32_e32 v136, v138
	v_permlane16_swap_b32_e32 v137, v139
	global_store_dwordx4 v216, v[136:139], s[98:99] offset:256
	s_mul_i32 s18, s19, 8
	s_add_u32 s98, s100, s18
	s_addc_u32 s99, s101, 0
	v_mul_f32_e32 v248, v24, v161
	v_mul_f32_e32 v249, v28, v161
	v_fma_f32 v240, v28, v160, -v248
	v_fma_f32 v244, v24, v160, v249
	v_mul_f32_e32 v248, v25, v163
	v_mul_f32_e32 v249, v29, v163
	v_fma_f32 v241, v29, v162, -v248
	v_fma_f32 v245, v25, v162, v249
	v_mul_f32_e32 v248, v26, v165
	v_mul_f32_e32 v249, v30, v165
	v_fma_f32 v242, v30, v164, -v248
	v_fma_f32 v246, v26, v164, v249
	v_mul_f32_e32 v248, v27, v167
	v_mul_f32_e32 v249, v31, v167
	v_fma_f32 v243, v31, v166, -v248
	v_fma_f32 v247, v27, v166, v249
	v_cvt_pk_bf16_f32 v204, v240, v241
	v_cvt_pk_bf16_f32 v205, v242, v243
	v_cvt_pk_bf16_f32 v206, v244, v245
; __device__ __forceinline__ unsigned cvt_pk_bf16(float lo, float hi) { unsigned r; asm volatile("v_cvt_pk_bf16_f32 %0, %1, %2" : "=v"(r) : "v"(lo), "v"(hi)); return r; }
; __device__ __forceinline__ void epi_store(const f32x4 (&acc)[2][2][4][2], const Unit& u, int wr, int wc, int fr, int fq, const EpiP& e) {
;     ...
;                 bf16_t* rowp = e.O + (size_t)row * e.ldo + c;
;                 u32x2 w0, w1; w0.x = cvt_pk_bf16(v0[0], v0[1]); w0.y = cvt_pk_bf16(v0[2], v0[3]); w1.x = cvt_pk_bf16(v1[0], v1[1]); w1.y = cvt_pk_bf16(v1[2], v1[3]);
;                 const bool odd = (fq & 1) != 0;
;                 const unsigned sx = odd ? w0.x : w1.x, sy = odd ? w0.y : w1.y;
;                 const unsigned rx = (unsigned)__shfl_xor((int)sx, 16), ry = (unsigned)__shfl_xor((int)sy, 16);
;                 u32x4 w; if (odd) { w.x = rx; w.y = ry; w.z = w1.x; w.w = w1.y; } else { w.x = w0.x; w.y = w0.y; w.z = rx; w.w = ry; }
;                 *(u32x4*)(rowp + (odd ? 12 : 0)) = w;
; __device__ __forceinline__ void gemm_phase(LAS unsigned char* lds, const GemmP g, const EpiP e) {
;     ...
;         if (!has_next) break;
	v_cvt_pk_bf16_f32 v207, v246, v247
	s_nop 1
	v_permlane16_swap_b32_e32 v204, v206
	v_permlane16_swap_b32_e32 v205, v207
	global_store_dwordx4 v216, v[204:207], s[98:99] offset:256
	s_mul_i32 s18, s19, 9
	s_add_u32 s98, s100, s18
	s_addc_u32 s99, s101, 0
	v_mul_f32_e32 v248, v16, v169
	v_mul_f32_e32 v249, v20, v169
	v_fma_f32 v240, v20, v168, -v248
	v_fma_f32 v244, v16, v168, v249
	v_mul_f32_e32 v248, v17, v171
	v_mul_f32_e32 v249, v21, v171
	v_fma_f32 v241, v21, v170, -v248
	v_fma_f32 v245, v17, v170, v249
	v_mul_f32_e32 v248, v18, v173
	v_mul_f32_e32 v249, v22, v173
	v_fma_f32 v242, v22, v172, -v248
	v_fma_f32 v246, v18, v172, v249
	v_mul_f32_e32 v248, v19, v175
	v_mul_f32_e32 v249, v23, v175
	v_fma_f32 v243, v23, v174, -v248
	v_fma_f32 v247, v19, v174, v249
	v_cvt_pk_bf16_f32 v132, v240, v241
	v_cvt_pk_bf16_f32 v133, v242, v243
	v_cvt_pk_bf16_f32 v134, v244, v245
	v_cvt_pk_bf16_f32 v135, v246, v247
	s_nop 1
	v_permlane16_swap_b32_e32 v132, v134
	v_permlane16_swap_b32_e32 v133, v135
	global_store_dwordx4 v216, v[132:135], s[98:99] offset:256
	s_mul_i32 s18, s19, 10
	s_add_u32 s98, s100, s18
	s_addc_u32 s99, s101, 0
	v_mul_f32_e32 v248, v8, v225
	v_mul_f32_e32 v249, v12, v225
	v_fma_f32 v240, v12, v224, -v248
	v_fma_f32 v244, v8, v224, v249
	v_mul_f32_e32 v248, v9, v227
	v_mul_f32_e32 v249, v13, v227
	v_fma_f32 v241, v13, v226, -v248
	v_fma_f32 v245, v9, v226, v249
	v_mul_f32_e32 v248, v10, v229
	v_mul_f32_e32 v249, v14, v229
	v_fma_f32 v242, v14, v228, -v248
	v_fma_f32 v246, v10, v228, v249
	v_mul_f32_e32 v248, v11, v231
	v_mul_f32_e32 v249, v15, v231
	v_fma_f32 v243, v15, v230, -v248
	v_fma_f32 v247, v11, v230, v249
	v_cvt_pk_bf16_f32 v136, v240, v241
	v_cvt_pk_bf16_f32 v137, v242, v243
	v_cvt_pk_bf16_f32 v138, v244, v245
	v_cvt_pk_bf16_f32 v139, v246, v247
	s_nop 1
	v_permlane16_swap_b32_e32 v136, v138
	v_permlane16_swap_b32_e32 v137, v139
	global_store_dwordx4 v216, v[136:139], s[98:99] offset:256
	s_mul_i32 s18, s19, 11
	s_add_u32 s98, s100, s18
	s_addc_u32 s99, s101, 0
	v_mul_f32_e32 v248, v0, v233
	v_mul_f32_e32 v249, v4, v233
	v_fma_f32 v240, v4, v232, -v248
	v_fma_f32 v244, v0, v232, v249
	v_mul_f32_e32 v248, v1, v235
	v_mul_f32_e32 v249, v5, v235
	v_fma_f32 v241, v5, v234, -v248
	v_fma_f32 v245, v1, v234, v249
	v_mul_f32_e32 v248, v2, v237
	v_mul_f32_e32 v249, v6, v237
	v_fma_f32 v242, v6, v236, -v248
	v_fma_f32 v246, v2, v236, v249
	v_mul_f32_e32 v248, v3, v239
	v_mul_f32_e32 v249, v7, v239
	v_fma_f32 v243, v7, v238, -v248
	v_fma_f32 v247, v3, v238, v249
	v_cvt_pk_bf16_f32 v204, v240, v241
	v_cvt_pk_bf16_f32 v205, v242, v243
	v_cvt_pk_bf16_f32 v206, v244, v245
	v_cvt_pk_bf16_f32 v207, v246, v247
	s_nop 1
	v_permlane16_swap_b32_e32 v204, v206
	v_permlane16_swap_b32_e32 v205, v207
	global_store_dwordx4 v216, v[204:207], s[98:99] offset:256
	s_branch .Lrp_end1
.Lrp_plain1:
	s_mov_b64 s[98:99], s[100:101]
	v_cvt_pk_bf16_f32 v132, v92, v93
	v_cvt_pk_bf16_f32 v133, v94, v95
	v_cvt_pk_bf16_f32 v134, v88, v89
	v_cvt_pk_bf16_f32 v135, v90, v91
	s_nop 1
	v_permlane16_swap_b32_e32 v132, v134
	v_permlane16_swap_b32_e32 v133, v135
	global_store_dwordx4 v216, v[132:135], s[98:99] offset:256
	s_mul_i32 s18, s19, 1
	s_add_u32 s98, s100, s18
	s_addc_u32 s99, s101, 0
	v_cvt_pk_bf16_f32 v136, v84, v85
	v_cvt_pk_bf16_f32 v137, v86, v87
	v_cvt_pk_bf16_f32 v138, v80, v81
	v_cvt_pk_bf16_f32 v139, v82, v83
	s_nop 1
	v_permlane16_swap_b32_e32 v136, v138
	v_permlane16_swap_b32_e32 v137, v139
	global_store_dwordx4 v216, v[136:139], s[98:99] offset:256
	s_mul_i32 s18, s19, 2
	s_add_u32 s98, s100, s18
	s_addc_u32 s99, s101, 0
	v_cvt_pk_bf16_f32 v204, v76, v77
	v_cvt_pk_bf16_f32 v205, v78, v79
	v_cvt_pk_bf16_f32 v206, v72, v73
	v_cvt_pk_bf16_f32 v207, v74, v75
	s_nop 1
	v_permlane16_swap_b32_e32 v204, v206
	v_permlane16_swap_b32_e32 v205, v207
	global_store_dwordx4 v216, v[204:207], s[98:99] offset:256
	s_mul_i32 s18, s19, 3
	s_add_u32 s98, s100, s18
	s_addc_u32 s99, s101, 0
	v_cvt_pk_bf16_f32 v132, v68, v69
	v_cvt_pk_bf16_f32 v133, v70, v71
	v_cvt_pk_bf16_f32 v134, v64, v65
	v_cvt_pk_bf16_f32 v135, v66, v67
	s_nop 1
	v_permlane16_swap_b32_e32 v132, v134
	v_permlane16_swap_b32_e32 v133, v135
	global_store_dwordx4 v216, v[132:135], s[98:99] offset:256
	s_mul_i32 s18, s19, 8
	s_add_u32 s98, s100, s18
	s_addc_u32 s99, s101, 0
	v_cvt_pk_bf16_f32 v136, v28, v29
	v_cvt_pk_bf16_f32 v137, v30, v31
	v_cvt_pk_bf16_f32 v138, v24, v25
	v_cvt_pk_bf16_f32 v139, v26, v27
	s_nop 1
	v_permlane16_swap_b32_e32 v136, v138
	v_permlane16_swap_b32_e32 v137, v139
	global_store_dwordx4 v216, v[136:139], s[98:99] offset:256
	s_mul_i32 s18, s19, 9
	s_add_u32 s98, s100, s18
	s_addc_u32 s99, s101, 0
	v_cvt_pk_bf16_f32 v204, v20, v21
	v_cvt_pk_bf16_f32 v205, v22, v23
	v_cvt_pk_bf16_f32 v206, v16, v17
	v_cvt_pk_bf16_f32 v207, v18, v19
	s_nop 1
	v_permlane16_swap_b32_e32 v204, v206
	v_permlane16_swap_b32_e32 v205, v207
	global_store_dwordx4 v216, v[204:207], s[98:99] offset:256
	s_mul_i32 s18, s19, 10
	s_add_u32 s98, s100, s18
	s_addc_u32 s99, s101, 0
	v_cvt_pk_bf16_f32 v132, v12, v13
	v_cvt_pk_bf16_f32 v133, v14, v15
	v_cvt_pk_bf16_f32 v134, v8, v9
	v_cvt_pk_bf16_f32 v135, v10, v11
	s_nop 1
	v_permlane16_swap_b32_e32 v132, v134
	v_permlane16_swap_b32_e32 v133, v135
	global_store_dwordx4 v216, v[132:135], s[98:99] offset:256
	s_mul_i32 s18, s19, 11
	s_add_u32 s98, s100, s18
	s_addc_u32 s99, s101, 0
	v_cvt_pk_bf16_f32 v136, v4, v5
	v_cvt_pk_bf16_f32 v137, v6, v7
	v_cvt_pk_bf16_f32 v138, v0, v1
	v_cvt_pk_bf16_f32 v139, v2, v3
	s_nop 1
	v_permlane16_swap_b32_e32 v136, v138
	v_permlane16_swap_b32_e32 v137, v139
	global_store_dwordx4 v216, v[136:139], s[98:99] offset:256
.Lrp_end1:
.LBB0_439:
	s_and_b64 vcc, exec, s[14:15]
	s_cbranch_vccnz .LBB0_371
	s_branch .LBB0_574
